# gemm_big K-loop: first LDS barrier moved up (after all fragment reads), next-tile ds_writes interleaved with the last 12 MFMAs of the tile (8 loops)
# speedup vs baseline: 1.0422x; 1.0176x over previous
; __device__ __forceinline__ void lds_barrier() { asm volatile("s_waitcnt lgkmcnt(0)\n\ts_barrier" ::: "memory"); }
; __device__ __forceinline__ f32x16 mfma32(bf16x8 a, bf16x8 b, f32x16 c) { return __builtin_amdgcn_mfma_f32_32x32x16_bf16(a, b, c, 0, 0, 0); }
; __device__ __forceinline__ void gemm_big(const bf16_t* __restrict__ A, long lda, const bf16_t* __restrict__ Bt, int K, f32x16 (&acc)[2][4], unsigned char* lds) {
;     ...
;     for (int kc = 0; kc < nk; ++kc) {
;         bf16x8 af[2][2], bfr[2][4];
;         af[0][0] = *(const bf16x8*)(Ac); af[0][1] = *(const bf16x8*)(Ac + 32 * GLD);
; #pragma unroll
;         for (int ni = 0; ni < 4; ++ni) bfr[0][ni] = *(const bf16x8*)(Bc + ni * 32 * GLD);
;         __builtin_amdgcn_s_setprio(3);
; #pragma unroll
;         for (int ks = 0; ks < 4; ++ks) {
;             const int cb = ks & 1, nb = cb ^ 1;
;             if (ks < 3) {
;                 af[nb][0] = *(const bf16x8*)(Ac + (ks + 1) * 16); af[nb][1] = *(const bf16x8*)(Ac + 32 * GLD + (ks + 1) * 16);
; #pragma unroll
;                 for (int ni = 0; ni < 4; ++ni) bfr[nb][ni] = *(const bf16x8*)(Bc + ni * 32 * GLD + (ks + 1) * 16);
;             }
;             __builtin_amdgcn_sched_barrier(0);
; #pragma unroll
;             for (int ni = 0; ni < 4; ++ni) { acc[0][ni] = mfma32(af[cb][0], bfr[cb][ni], acc[0][ni]); acc[1][ni] = mfma32(af[cb][1], bfr[cb][ni], acc[1][ni]); }
;             __builtin_amdgcn_sched_barrier(0);
;         }
;         __builtin_amdgcn_s_setprio(0);
;         lds_barrier();
;         if (kc + 1 < nk) {
;             lstore();
;             if (kc + 2 < nk) gload(kc + 2);
;             lds_barrier();
;         }
.LBB0_56:
	s_cmp_gt_u32 s13, 42
	s_cbranch_scc1 .Lmy_gorig_8
	ds_read_b128 v[190:193], v187
	ds_read_b128 v[194:197], v187 offset:4608
	ds_read_b128 v[198:201], v188 offset:18432
	ds_read_b128 v[202:205], v188 offset:23040
	ds_read_b128 v[206:209], v188 offset:27648
	ds_read_b128 v[210:213], v188 offset:32256
	s_setprio 3
	ds_read_b128 v[214:217], v187 offset:32
	ds_read_b128 v[218:221], v187 offset:4640
	ds_read_b128 v[224:227], v188 offset:18464
	ds_read_b128 v[234:237], v188 offset:23072
	ds_read_b128 v[238:241], v188 offset:27680
	ds_read_b128 v[242:245], v188 offset:32288
	s_waitcnt lgkmcnt(9)
	v_mfma_f32_32x32x16_bf16 v[114:129], v[190:193], v[198:201], v[114:129]
	v_mfma_f32_32x32x16_bf16 v[50:65], v[194:197], v[198:201], v[50:65]
	s_waitcnt lgkmcnt(8)
	v_mfma_f32_32x32x16_bf16 v[98:113], v[190:193], v[202:205], v[98:113]
	v_mfma_f32_32x32x16_bf16 v[34:49], v[194:197], v[202:205], v[34:49]
	s_waitcnt lgkmcnt(7)
	v_mfma_f32_32x32x16_bf16 v[82:97], v[190:193], v[206:209], v[82:97]
	v_mfma_f32_32x32x16_bf16 v[18:33], v[194:197], v[206:209], v[18:33]
	s_waitcnt lgkmcnt(6)
	v_mfma_f32_32x32x16_bf16 v[66:81], v[190:193], v[210:213], v[66:81]
	v_mfma_f32_32x32x16_bf16 v[2:17], v[194:197], v[210:213], v[2:17]
	ds_read_b128 v[190:193], v187 offset:64
	ds_read_b128 v[194:197], v187 offset:4672
	ds_read_b128 v[198:201], v188 offset:18496
	ds_read_b128 v[202:205], v188 offset:23104
	ds_read_b128 v[206:209], v188 offset:27712
	ds_read_b128 v[210:213], v188 offset:32320
	s_waitcnt lgkmcnt(9)
	v_mfma_f32_32x32x16_bf16 v[114:129], v[214:217], v[224:227], v[114:129]
	v_mfma_f32_32x32x16_bf16 v[50:65], v[218:221], v[224:227], v[50:65]
	s_waitcnt lgkmcnt(8)
	v_mfma_f32_32x32x16_bf16 v[98:113], v[214:217], v[234:237], v[98:113]
	v_mfma_f32_32x32x16_bf16 v[34:49], v[218:221], v[234:237], v[34:49]
	s_waitcnt lgkmcnt(7)
	v_mfma_f32_32x32x16_bf16 v[82:97], v[214:217], v[238:241], v[82:97]
	v_mfma_f32_32x32x16_bf16 v[18:33], v[218:221], v[238:241], v[18:33]
	s_waitcnt lgkmcnt(6)
	v_mfma_f32_32x32x16_bf16 v[66:81], v[214:217], v[242:245], v[66:81]
	v_mfma_f32_32x32x16_bf16 v[2:17], v[218:221], v[242:245], v[2:17]
	ds_read_b128 v[214:217], v187 offset:96
	ds_read_b128 v[218:221], v187 offset:4704
	ds_read_b128 v[224:227], v188 offset:18528
	ds_read_b128 v[234:237], v188 offset:23136
	ds_read_b128 v[238:241], v188 offset:27744
	ds_read_b128 v[242:245], v188 offset:32352
	s_waitcnt lgkmcnt(9)
	v_mfma_f32_32x32x16_bf16 v[114:129], v[190:193], v[198:201], v[114:129]
	v_mfma_f32_32x32x16_bf16 v[50:65], v[194:197], v[198:201], v[50:65]
	s_waitcnt lgkmcnt(8)
	v_mfma_f32_32x32x16_bf16 v[98:113], v[190:193], v[202:205], v[98:113]
	v_mfma_f32_32x32x16_bf16 v[34:49], v[194:197], v[202:205], v[34:49]
	s_waitcnt lgkmcnt(0)
	s_barrier
	v_mfma_f32_32x32x16_bf16 v[82:97], v[190:193], v[206:209], v[82:97]
	s_waitcnt vmcnt(9)
	ds_write_b128 v189, v[130:133]
	v_mfma_f32_32x32x16_bf16 v[18:33], v[194:197], v[206:209], v[18:33]
	ds_write_b128 v189, v[134:137] offset:4608
	v_mfma_f32_32x32x16_bf16 v[66:81], v[190:193], v[210:213], v[66:81]
	ds_write_b128 v189, v[138:141] offset:9216
	v_mfma_f32_32x32x16_bf16 v[2:17], v[194:197], v[210:213], v[2:17]
	s_waitcnt vmcnt(7)
	ds_write_b128 v189, v[142:145] offset:13824
	v_mfma_f32_32x32x16_bf16 v[114:129], v[214:217], v[224:227], v[114:129]
	ds_write_b128 v189, v[146:149] offset:18432
	v_mfma_f32_32x32x16_bf16 v[50:65], v[218:221], v[224:227], v[50:65]
	s_waitcnt vmcnt(6)
	ds_write_b128 v189, v[150:153] offset:23040
	v_mfma_f32_32x32x16_bf16 v[98:113], v[214:217], v[234:237], v[98:113]
	s_waitcnt vmcnt(5)
	ds_write_b128 v189, v[154:157] offset:27648
	v_mfma_f32_32x32x16_bf16 v[34:49], v[218:221], v[234:237], v[34:49]
	s_waitcnt vmcnt(4)
	ds_write_b128 v189, v[158:161] offset:32256
	v_mfma_f32_32x32x16_bf16 v[82:97], v[214:217], v[238:241], v[82:97]
	s_waitcnt vmcnt(3)
	ds_write_b128 v189, v[162:165] offset:36864
	v_mfma_f32_32x32x16_bf16 v[18:33], v[218:221], v[238:241], v[18:33]
	s_waitcnt vmcnt(2)
	ds_write_b128 v189, v[166:169] offset:41472
	v_mfma_f32_32x32x16_bf16 v[66:81], v[214:217], v[242:245], v[66:81]
	s_waitcnt vmcnt(1)
	ds_write_b128 v189, v[170:173] offset:46080
	v_mfma_f32_32x32x16_bf16 v[2:17], v[218:221], v[242:245], v[2:17]
	s_waitcnt vmcnt(0)
	ds_write_b128 v189, v[174:177] offset:50688
	s_cmpk_eq_i32 s4, 0x1500
	s_cbranch_scc1 .Lmy_gnold_8
	v_lshl_add_u64 v[138:139], v[184:185], 0, s[4:5]
	v_add_co_u32_e32 v130, vcc, 0x78a8000, v138
	v_lshl_add_u64 v[170:171], v[182:183], 0, s[4:5]
	s_nop 0
	v_addc_co_u32_e32 v131, vcc, 0, v139, vcc
	v_add_co_u32_e32 v134, vcc, 0x78d4000, v138
	s_nop 1
	v_addc_co_u32_e32 v135, vcc, 0, v139, vcc
	v_add_co_u32_e32 v140, vcc, 0x7900000, v138
	global_load_dwordx4 v[130:133], v[130:131], off offset:256
	s_nop 0
	global_load_dwordx4 v[134:137], v[134:135], off offset:256
	v_addc_co_u32_e32 v141, vcc, 0, v139, vcc
	v_add_co_u32_e32 v142, vcc, 0x792c000, v138
	s_nop 1
	v_addc_co_u32_e32 v143, vcc, 0, v139, vcc
	v_add_co_u32_e32 v146, vcc, 0x3328000, v170
	global_load_dwordx4 v[138:141], v[140:141], off offset:256
	s_nop 0
	global_load_dwordx4 v[142:145], v[142:143], off offset:256
	v_addc_co_u32_e32 v147, vcc, 0, v171, vcc
	v_add_co_u32_e32 v150, vcc, 0x3354000, v170
	s_nop 1
	v_addc_co_u32_e32 v151, vcc, 0, v171, vcc
	v_add_co_u32_e32 v154, vcc, 0x3380000, v170
	global_load_dwordx4 v[146:149], v[146:147], off offset:256
	s_nop 0
	global_load_dwordx4 v[150:153], v[150:151], off offset:256
	v_addc_co_u32_e32 v155, vcc, 0, v171, vcc
	v_add_co_u32_e32 v158, vcc, 0x33ac000, v170
	s_nop 1
	v_addc_co_u32_e32 v159, vcc, 0, v171, vcc
	v_add_co_u32_e32 v162, vcc, 0x33d8000, v170
	global_load_dwordx4 v[154:157], v[154:155], off offset:256
	s_nop 0
	global_load_dwordx4 v[158:161], v[158:159], off offset:256
	v_addc_co_u32_e32 v163, vcc, 0, v171, vcc
	v_add_co_u32_e32 v166, vcc, 0x3404000, v170
	s_nop 1
	v_addc_co_u32_e32 v167, vcc, 0, v171, vcc
	v_add_co_u32_e32 v172, vcc, 0x3430000, v170
	global_load_dwordx4 v[162:165], v[162:163], off offset:256
	s_nop 0
	global_load_dwordx4 v[166:169], v[166:167], off offset:256
	v_addc_co_u32_e32 v173, vcc, 0, v171, vcc
	v_add_co_u32_e32 v174, vcc, 0x345c000, v170
	s_nop 1
	v_addc_co_u32_e32 v175, vcc, 0, v171, vcc
	global_load_dwordx4 v[170:173], v[172:173], off offset:256
	s_nop 0
	global_load_dwordx4 v[174:177], v[174:175], off offset:256
.Lmy_gnold_8:
	s_setprio 0
	s_branch .LBB0_54

; __device__ __forceinline__ void lds_barrier() { asm volatile("s_waitcnt lgkmcnt(0)\n\ts_barrier" ::: "memory"); }
; __device__ __forceinline__ f32x16 mfma32(bf16x8 a, bf16x8 b, f32x16 c) { return __builtin_amdgcn_mfma_f32_32x32x16_bf16(a, b, c, 0, 0, 0); }
; __device__ __forceinline__ void gemm_big(const bf16_t* __restrict__ A, long lda, const bf16_t* __restrict__ Bt, int K, f32x16 (&acc)[2][4], unsigned char* lds) {
;     ...
;     for (int kc = 0; kc < nk; ++kc) {
;         bf16x8 af[2][2], bfr[2][4];
;         af[0][0] = *(const bf16x8*)(Ac); af[0][1] = *(const bf16x8*)(Ac + 32 * GLD);
; #pragma unroll
;         for (int ni = 0; ni < 4; ++ni) bfr[0][ni] = *(const bf16x8*)(Bc + ni * 32 * GLD);
;         __builtin_amdgcn_s_setprio(3);
; #pragma unroll
;         for (int ks = 0; ks < 4; ++ks) {
;             const int cb = ks & 1, nb = cb ^ 1;
;             if (ks < 3) {
;                 af[nb][0] = *(const bf16x8*)(Ac + (ks + 1) * 16); af[nb][1] = *(const bf16x8*)(Ac + 32 * GLD + (ks + 1) * 16);
; #pragma unroll
;                 for (int ni = 0; ni < 4; ++ni) bfr[nb][ni] = *(const bf16x8*)(Bc + ni * 32 * GLD + (ks + 1) * 16);
;             }
;             __builtin_amdgcn_sched_barrier(0);
; #pragma unroll
;             for (int ni = 0; ni < 4; ++ni) { acc[0][ni] = mfma32(af[cb][0], bfr[cb][ni], acc[0][ni]); acc[1][ni] = mfma32(af[cb][1], bfr[cb][ni], acc[1][ni]); }
;             __builtin_amdgcn_sched_barrier(0);
;         }
;         __builtin_amdgcn_s_setprio(0);
;         lds_barrier();
;         if (kc + 1 < nk) {
;             lstore();
;             if (kc + 2 < nk) gload(kc + 2);
;             lds_barrier();
;         }
.LBB0_67:
	s_cmp_gt_u32 s5, 14
	s_cbranch_scc1 .Lmy_gorig_7
	ds_read_b128 v[190:193], v187
	ds_read_b128 v[194:197], v187 offset:4608
	ds_read_b128 v[198:201], v188 offset:18432
	ds_read_b128 v[202:205], v188 offset:23040
	ds_read_b128 v[206:209], v188 offset:27648
	ds_read_b128 v[210:213], v188 offset:32256
	s_setprio 3
	ds_read_b128 v[214:217], v187 offset:32
	ds_read_b128 v[218:221], v187 offset:4640
	ds_read_b128 v[224:227], v188 offset:18464
	ds_read_b128 v[234:237], v188 offset:23072
	ds_read_b128 v[238:241], v188 offset:27680
	ds_read_b128 v[242:245], v188 offset:32288
	s_waitcnt lgkmcnt(9)
	v_mfma_f32_32x32x16_bf16 v[114:129], v[190:193], v[198:201], v[114:129]
	v_mfma_f32_32x32x16_bf16 v[82:97], v[194:197], v[198:201], v[82:97]
	s_waitcnt lgkmcnt(8)
	v_mfma_f32_32x32x16_bf16 v[98:113], v[190:193], v[202:205], v[98:113]
	v_mfma_f32_32x32x16_bf16 v[66:81], v[194:197], v[202:205], v[66:81]
	s_waitcnt lgkmcnt(7)
	v_mfma_f32_32x32x16_bf16 v[50:65], v[190:193], v[206:209], v[50:65]
	v_mfma_f32_32x32x16_bf16 v[18:33], v[194:197], v[206:209], v[18:33]
	s_waitcnt lgkmcnt(6)
	v_mfma_f32_32x32x16_bf16 v[34:49], v[190:193], v[210:213], v[34:49]
	v_mfma_f32_32x32x16_bf16 v[2:17], v[194:197], v[210:213], v[2:17]
	ds_read_b128 v[190:193], v187 offset:64
	ds_read_b128 v[194:197], v187 offset:4672
	ds_read_b128 v[198:201], v188 offset:18496
	ds_read_b128 v[202:205], v188 offset:23104
	ds_read_b128 v[206:209], v188 offset:27712
	ds_read_b128 v[210:213], v188 offset:32320
	s_waitcnt lgkmcnt(9)
	v_mfma_f32_32x32x16_bf16 v[114:129], v[214:217], v[224:227], v[114:129]
	v_mfma_f32_32x32x16_bf16 v[82:97], v[218:221], v[224:227], v[82:97]
	s_waitcnt lgkmcnt(8)
	v_mfma_f32_32x32x16_bf16 v[98:113], v[214:217], v[234:237], v[98:113]
	v_mfma_f32_32x32x16_bf16 v[66:81], v[218:221], v[234:237], v[66:81]
	s_waitcnt lgkmcnt(7)
	v_mfma_f32_32x32x16_bf16 v[50:65], v[214:217], v[238:241], v[50:65]
	v_mfma_f32_32x32x16_bf16 v[18:33], v[218:221], v[238:241], v[18:33]
	s_waitcnt lgkmcnt(6)
	v_mfma_f32_32x32x16_bf16 v[34:49], v[214:217], v[242:245], v[34:49]
	v_mfma_f32_32x32x16_bf16 v[2:17], v[218:221], v[242:245], v[2:17]
	ds_read_b128 v[214:217], v187 offset:96
	ds_read_b128 v[218:221], v187 offset:4704
	ds_read_b128 v[224:227], v188 offset:18528
	ds_read_b128 v[234:237], v188 offset:23136
	ds_read_b128 v[238:241], v188 offset:27744
	ds_read_b128 v[242:245], v188 offset:32352
	s_waitcnt lgkmcnt(9)
	v_mfma_f32_32x32x16_bf16 v[114:129], v[190:193], v[198:201], v[114:129]
	v_mfma_f32_32x32x16_bf16 v[82:97], v[194:197], v[198:201], v[82:97]
	s_waitcnt lgkmcnt(8)
	v_mfma_f32_32x32x16_bf16 v[98:113], v[190:193], v[202:205], v[98:113]
	v_mfma_f32_32x32x16_bf16 v[66:81], v[194:197], v[202:205], v[66:81]
	s_waitcnt lgkmcnt(0)
	s_barrier
	v_mfma_f32_32x32x16_bf16 v[50:65], v[190:193], v[206:209], v[50:65]
	s_waitcnt vmcnt(9)
	ds_write_b128 v189, v[130:133]
	v_mfma_f32_32x32x16_bf16 v[18:33], v[194:197], v[206:209], v[18:33]
	ds_write_b128 v189, v[134:137] offset:4608
	v_mfma_f32_32x32x16_bf16 v[34:49], v[190:193], v[210:213], v[34:49]
	ds_write_b128 v189, v[138:141] offset:9216
	v_mfma_f32_32x32x16_bf16 v[2:17], v[194:197], v[210:213], v[2:17]
	s_waitcnt vmcnt(7)
	ds_write_b128 v189, v[142:145] offset:13824
	v_mfma_f32_32x32x16_bf16 v[114:129], v[214:217], v[224:227], v[114:129]
	ds_write_b128 v189, v[146:149] offset:18432
	v_mfma_f32_32x32x16_bf16 v[82:97], v[218:221], v[224:227], v[82:97]
	s_waitcnt vmcnt(6)
	ds_write_b128 v189, v[150:153] offset:23040
	v_mfma_f32_32x32x16_bf16 v[98:113], v[214:217], v[234:237], v[98:113]
	s_waitcnt vmcnt(5)
	ds_write_b128 v189, v[154:157] offset:27648
	v_mfma_f32_32x32x16_bf16 v[66:81], v[218:221], v[234:237], v[66:81]
	s_waitcnt vmcnt(4)
	ds_write_b128 v189, v[158:161] offset:32256
	v_mfma_f32_32x32x16_bf16 v[50:65], v[214:217], v[238:241], v[50:65]
	s_waitcnt vmcnt(3)
	ds_write_b128 v189, v[162:165] offset:36864
	v_mfma_f32_32x32x16_bf16 v[18:33], v[218:221], v[238:241], v[18:33]
	s_waitcnt vmcnt(2)
	ds_write_b128 v189, v[166:169] offset:41472
	v_mfma_f32_32x32x16_bf16 v[34:49], v[214:217], v[242:245], v[34:49]
	s_waitcnt vmcnt(1)
	ds_write_b128 v189, v[170:173] offset:46080
	v_mfma_f32_32x32x16_bf16 v[2:17], v[218:221], v[242:245], v[2:17]
	s_waitcnt vmcnt(0)
	ds_write_b128 v189, v[174:177] offset:50688
	s_cmpk_eq_i32 s6, 0x700
	s_cbranch_scc1 .Lmy_gnold_7
	v_lshl_add_u64 v[138:139], v[184:185], 0, s[6:7]
	v_add_co_u32_e32 v130, vcc, 0x38a8000, v138
	v_lshl_add_u64 v[170:171], v[182:183], 0, s[6:7]
	s_nop 0
	v_addc_co_u32_e32 v131, vcc, 0, v139, vcc
	v_add_co_u32_e32 v134, vcc, 0x38b8000, v138
	s_nop 1
	v_addc_co_u32_e32 v135, vcc, 0, v139, vcc
	v_add_co_u32_e32 v140, vcc, 0x38c8000, v138
	global_load_dwordx4 v[130:133], v[130:131], off offset:256
	s_nop 0
	global_load_dwordx4 v[134:137], v[134:135], off offset:256
	v_addc_co_u32_e32 v141, vcc, 0, v139, vcc
	v_add_co_u32_e32 v142, vcc, 0x38d8000, v138
	s_nop 1
	v_addc_co_u32_e32 v143, vcc, 0, v139, vcc
	v_add_co_u32_e32 v146, vcc, 0x2828000, v170
	global_load_dwordx4 v[138:141], v[140:141], off offset:256
	s_nop 0
	global_load_dwordx4 v[142:145], v[142:143], off offset:256
	v_addc_co_u32_e32 v147, vcc, 0, v171, vcc
	v_add_co_u32_e32 v150, vcc, 0x2838000, v170
	s_nop 1
	v_addc_co_u32_e32 v151, vcc, 0, v171, vcc
	v_add_co_u32_e32 v154, vcc, 0x2848000, v170
	global_load_dwordx4 v[146:149], v[146:147], off offset:256
	s_nop 0
	global_load_dwordx4 v[150:153], v[150:151], off offset:256
	v_addc_co_u32_e32 v155, vcc, 0, v171, vcc
	v_add_co_u32_e32 v158, vcc, 0x2858000, v170
	s_nop 1
	v_addc_co_u32_e32 v159, vcc, 0, v171, vcc
	v_add_co_u32_e32 v162, vcc, 0x2868000, v170
	global_load_dwordx4 v[154:157], v[154:155], off offset:256
	s_nop 0
	global_load_dwordx4 v[158:161], v[158:159], off offset:256
	v_addc_co_u32_e32 v163, vcc, 0, v171, vcc
	v_add_co_u32_e32 v166, vcc, 0x2878000, v170
	s_nop 1
	v_addc_co_u32_e32 v167, vcc, 0, v171, vcc
	v_add_co_u32_e32 v172, vcc, 0x2888000, v170
	global_load_dwordx4 v[162:165], v[162:163], off offset:256
	s_nop 0
	global_load_dwordx4 v[166:169], v[166:167], off offset:256
	v_addc_co_u32_e32 v173, vcc, 0, v171, vcc
	v_add_co_u32_e32 v174, vcc, 0x2898000, v170
	s_nop 1
	v_addc_co_u32_e32 v175, vcc, 0, v171, vcc
	global_load_dwordx4 v[170:173], v[172:173], off offset:256
	s_nop 0
	global_load_dwordx4 v[174:177], v[174:175], off offset:256

; __device__ __forceinline__ void lds_barrier() { asm volatile("s_waitcnt lgkmcnt(0)\n\ts_barrier" ::: "memory"); }
; __device__ __forceinline__ f32x16 mfma32(bf16x8 a, bf16x8 b, f32x16 c) { return __builtin_amdgcn_mfma_f32_32x32x16_bf16(a, b, c, 0, 0, 0); }
; __device__ __forceinline__ void gemm_big(const bf16_t* __restrict__ A, long lda, const bf16_t* __restrict__ Bt, int K, f32x16 (&acc)[2][4], unsigned char* lds) {
;     ...
;     for (int kc = 0; kc < nk; ++kc) {
;         bf16x8 af[2][2], bfr[2][4];
;         af[0][0] = *(const bf16x8*)(Ac); af[0][1] = *(const bf16x8*)(Ac + 32 * GLD);
; #pragma unroll
;         for (int ni = 0; ni < 4; ++ni) bfr[0][ni] = *(const bf16x8*)(Bc + ni * 32 * GLD);
;         __builtin_amdgcn_s_setprio(3);
; #pragma unroll
;         for (int ks = 0; ks < 4; ++ks) {
;             const int cb = ks & 1, nb = cb ^ 1;
;             if (ks < 3) {
;                 af[nb][0] = *(const bf16x8*)(Ac + (ks + 1) * 16); af[nb][1] = *(const bf16x8*)(Ac + 32 * GLD + (ks + 1) * 16);
; #pragma unroll
;                 for (int ni = 0; ni < 4; ++ni) bfr[nb][ni] = *(const bf16x8*)(Bc + ni * 32 * GLD + (ks + 1) * 16);
;             }
;             __builtin_amdgcn_sched_barrier(0);
; #pragma unroll
;             for (int ni = 0; ni < 4; ++ni) { acc[0][ni] = mfma32(af[cb][0], bfr[cb][ni], acc[0][ni]); acc[1][ni] = mfma32(af[cb][1], bfr[cb][ni], acc[1][ni]); }
;             __builtin_amdgcn_sched_barrier(0);
;         }
;         __builtin_amdgcn_s_setprio(0);
;         lds_barrier();
;         if (kc + 1 < nk) {
;             lstore();
;             if (kc + 2 < nk) gload(kc + 2);
;             lds_barrier();
;         }
.LBB0_84:
	s_cmp_gt_u32 s5, 14
	s_cbranch_scc1 .Lmy_gorig_6
	ds_read_b128 v[190:193], v187
	ds_read_b128 v[194:197], v187 offset:4608
	ds_read_b128 v[198:201], v188 offset:18432
	ds_read_b128 v[202:205], v188 offset:23040
	ds_read_b128 v[206:209], v188 offset:27648
	ds_read_b128 v[210:213], v188 offset:32256
	s_setprio 3
	ds_read_b128 v[214:217], v187 offset:32
	ds_read_b128 v[218:221], v187 offset:4640
	ds_read_b128 v[224:227], v188 offset:18464
	ds_read_b128 v[234:237], v188 offset:23072
	ds_read_b128 v[238:241], v188 offset:27680
	ds_read_b128 v[242:245], v188 offset:32288
	s_waitcnt lgkmcnt(9)
	v_mfma_f32_32x32x16_bf16 v[114:129], v[190:193], v[198:201], v[114:129]
	v_mfma_f32_32x32x16_bf16 v[50:65], v[194:197], v[198:201], v[50:65]
	s_waitcnt lgkmcnt(8)
	v_mfma_f32_32x32x16_bf16 v[98:113], v[190:193], v[202:205], v[98:113]
	v_mfma_f32_32x32x16_bf16 v[34:49], v[194:197], v[202:205], v[34:49]
	s_waitcnt lgkmcnt(7)
	v_mfma_f32_32x32x16_bf16 v[82:97], v[190:193], v[206:209], v[82:97]
	v_mfma_f32_32x32x16_bf16 v[18:33], v[194:197], v[206:209], v[18:33]
	s_waitcnt lgkmcnt(6)
	v_mfma_f32_32x32x16_bf16 v[66:81], v[190:193], v[210:213], v[66:81]
	v_mfma_f32_32x32x16_bf16 v[2:17], v[194:197], v[210:213], v[2:17]
	ds_read_b128 v[190:193], v187 offset:64
	ds_read_b128 v[194:197], v187 offset:4672
	ds_read_b128 v[198:201], v188 offset:18496
	ds_read_b128 v[202:205], v188 offset:23104
	ds_read_b128 v[206:209], v188 offset:27712
	ds_read_b128 v[210:213], v188 offset:32320
	s_waitcnt lgkmcnt(9)
	v_mfma_f32_32x32x16_bf16 v[114:129], v[214:217], v[224:227], v[114:129]
	v_mfma_f32_32x32x16_bf16 v[50:65], v[218:221], v[224:227], v[50:65]
	s_waitcnt lgkmcnt(8)
	v_mfma_f32_32x32x16_bf16 v[98:113], v[214:217], v[234:237], v[98:113]
	v_mfma_f32_32x32x16_bf16 v[34:49], v[218:221], v[234:237], v[34:49]
	s_waitcnt lgkmcnt(7)
	v_mfma_f32_32x32x16_bf16 v[82:97], v[214:217], v[238:241], v[82:97]
	v_mfma_f32_32x32x16_bf16 v[18:33], v[218:221], v[238:241], v[18:33]
	s_waitcnt lgkmcnt(6)
	v_mfma_f32_32x32x16_bf16 v[66:81], v[214:217], v[242:245], v[66:81]
	v_mfma_f32_32x32x16_bf16 v[2:17], v[218:221], v[242:245], v[2:17]
	ds_read_b128 v[214:217], v187 offset:96
	ds_read_b128 v[218:221], v187 offset:4704
	ds_read_b128 v[224:227], v188 offset:18528
	ds_read_b128 v[234:237], v188 offset:23136
	ds_read_b128 v[238:241], v188 offset:27744
	ds_read_b128 v[242:245], v188 offset:32352
	s_waitcnt lgkmcnt(9)
	v_mfma_f32_32x32x16_bf16 v[114:129], v[190:193], v[198:201], v[114:129]
	v_mfma_f32_32x32x16_bf16 v[50:65], v[194:197], v[198:201], v[50:65]
	s_waitcnt lgkmcnt(8)
	v_mfma_f32_32x32x16_bf16 v[98:113], v[190:193], v[202:205], v[98:113]
	v_mfma_f32_32x32x16_bf16 v[34:49], v[194:197], v[202:205], v[34:49]
	s_waitcnt lgkmcnt(0)
	s_barrier
	v_mfma_f32_32x32x16_bf16 v[82:97], v[190:193], v[206:209], v[82:97]
	s_waitcnt vmcnt(9)
	ds_write_b128 v189, v[130:133]
	v_mfma_f32_32x32x16_bf16 v[18:33], v[194:197], v[206:209], v[18:33]
	ds_write_b128 v189, v[134:137] offset:4608
	v_mfma_f32_32x32x16_bf16 v[66:81], v[190:193], v[210:213], v[66:81]
	ds_write_b128 v189, v[138:141] offset:9216
	v_mfma_f32_32x32x16_bf16 v[2:17], v[194:197], v[210:213], v[2:17]
	s_waitcnt vmcnt(7)
	ds_write_b128 v189, v[142:145] offset:13824
	v_mfma_f32_32x32x16_bf16 v[114:129], v[214:217], v[224:227], v[114:129]
	ds_write_b128 v189, v[146:149] offset:18432
	v_mfma_f32_32x32x16_bf16 v[50:65], v[218:221], v[224:227], v[50:65]
	s_waitcnt vmcnt(6)
	ds_write_b128 v189, v[150:153] offset:23040
	v_mfma_f32_32x32x16_bf16 v[98:113], v[214:217], v[234:237], v[98:113]
	s_waitcnt vmcnt(5)
	ds_write_b128 v189, v[154:157] offset:27648
	v_mfma_f32_32x32x16_bf16 v[34:49], v[218:221], v[234:237], v[34:49]
	s_waitcnt vmcnt(4)
	ds_write_b128 v189, v[158:161] offset:32256
	v_mfma_f32_32x32x16_bf16 v[82:97], v[214:217], v[238:241], v[82:97]
	s_waitcnt vmcnt(3)
	ds_write_b128 v189, v[162:165] offset:36864
	v_mfma_f32_32x32x16_bf16 v[18:33], v[218:221], v[238:241], v[18:33]
	s_waitcnt vmcnt(2)
	ds_write_b128 v189, v[166:169] offset:41472
	v_mfma_f32_32x32x16_bf16 v[66:81], v[214:217], v[242:245], v[66:81]
	s_waitcnt vmcnt(1)
	ds_write_b128 v189, v[170:173] offset:46080
	v_mfma_f32_32x32x16_bf16 v[2:17], v[218:221], v[242:245], v[2:17]
	s_waitcnt vmcnt(0)
	ds_write_b128 v189, v[174:177] offset:50688
	s_cmpk_eq_i32 s6, 0x700
	s_cbranch_scc1 .Lmy_gnold_6
	v_lshl_add_u64 v[138:139], v[184:185], 0, s[6:7]
	v_add_co_u32_e32 v130, vcc, 0x14948000, v138
	v_lshl_add_u64 v[170:171], v[182:183], 0, s[6:7]
	s_nop 0
	v_addc_co_u32_e32 v131, vcc, 0, v139, vcc
	v_add_co_u32_e32 v134, vcc, 0x14958000, v138
	s_nop 1
	v_addc_co_u32_e32 v135, vcc, 0, v139, vcc
	v_add_co_u32_e32 v140, vcc, 0x14968000, v138
	global_load_dwordx4 v[130:133], v[130:131], off offset:256
	s_nop 0
	global_load_dwordx4 v[134:137], v[134:135], off offset:256
	v_addc_co_u32_e32 v141, vcc, 0, v139, vcc
	v_add_co_u32_e32 v142, vcc, 0x14978000, v138
	s_nop 1
	v_addc_co_u32_e32 v143, vcc, 0, v139, vcc
	v_add_co_u32_e32 v146, vcc, 0x2628000, v170
	global_load_dwordx4 v[138:141], v[140:141], off offset:256
	s_nop 0
	global_load_dwordx4 v[142:145], v[142:143], off offset:256
	v_addc_co_u32_e32 v147, vcc, 0, v171, vcc
	v_add_co_u32_e32 v150, vcc, 0x2638000, v170
	s_nop 1
	v_addc_co_u32_e32 v151, vcc, 0, v171, vcc
	v_add_co_u32_e32 v154, vcc, 0x2648000, v170
	global_load_dwordx4 v[146:149], v[146:147], off offset:256
	s_nop 0
	global_load_dwordx4 v[150:153], v[150:151], off offset:256
	v_addc_co_u32_e32 v155, vcc, 0, v171, vcc
	v_add_co_u32_e32 v158, vcc, 0x2658000, v170
	s_nop 1
	v_addc_co_u32_e32 v159, vcc, 0, v171, vcc
	v_add_co_u32_e32 v162, vcc, 0x2668000, v170
	global_load_dwordx4 v[154:157], v[154:155], off offset:256
	s_nop 0
	global_load_dwordx4 v[158:161], v[158:159], off offset:256
	v_addc_co_u32_e32 v163, vcc, 0, v171, vcc
	v_add_co_u32_e32 v166, vcc, 0x2678000, v170
	s_nop 1
	v_addc_co_u32_e32 v167, vcc, 0, v171, vcc
	v_add_co_u32_e32 v172, vcc, 0x2688000, v170
	global_load_dwordx4 v[162:165], v[162:163], off offset:256
	s_nop 0
	global_load_dwordx4 v[166:169], v[166:167], off offset:256
	v_addc_co_u32_e32 v173, vcc, 0, v171, vcc
	v_add_co_u32_e32 v174, vcc, 0x2698000, v170
	s_nop 1
	v_addc_co_u32_e32 v175, vcc, 0, v171, vcc
	global_load_dwordx4 v[170:173], v[172:173], off offset:256
	s_nop 0
	global_load_dwordx4 v[174:177], v[174:175], off offset:256

; __device__ __forceinline__ void lds_barrier() { asm volatile("s_waitcnt lgkmcnt(0)\n\ts_barrier" ::: "memory"); }
; __device__ __forceinline__ f32x16 mfma32(bf16x8 a, bf16x8 b, f32x16 c) { return __builtin_amdgcn_mfma_f32_32x32x16_bf16(a, b, c, 0, 0, 0); }
; __device__ __forceinline__ void gemm_big(const bf16_t* __restrict__ A, long lda, const bf16_t* __restrict__ Bt, int K, f32x16 (&acc)[2][4], unsigned char* lds) {
;     ...
;     for (int kc = 0; kc < nk; ++kc) {
;         bf16x8 af[2][2], bfr[2][4];
;         af[0][0] = *(const bf16x8*)(Ac); af[0][1] = *(const bf16x8*)(Ac + 32 * GLD);
; #pragma unroll
;         for (int ni = 0; ni < 4; ++ni) bfr[0][ni] = *(const bf16x8*)(Bc + ni * 32 * GLD);
;         __builtin_amdgcn_s_setprio(3);
; #pragma unroll
;         for (int ks = 0; ks < 4; ++ks) {
;             const int cb = ks & 1, nb = cb ^ 1;
;             if (ks < 3) {
;                 af[nb][0] = *(const bf16x8*)(Ac + (ks + 1) * 16); af[nb][1] = *(const bf16x8*)(Ac + 32 * GLD + (ks + 1) * 16);
; #pragma unroll
;                 for (int ni = 0; ni < 4; ++ni) bfr[nb][ni] = *(const bf16x8*)(Bc + ni * 32 * GLD + (ks + 1) * 16);
;             }
;             __builtin_amdgcn_sched_barrier(0);
; #pragma unroll
;             for (int ni = 0; ni < 4; ++ni) { acc[0][ni] = mfma32(af[cb][0], bfr[cb][ni], acc[0][ni]); acc[1][ni] = mfma32(af[cb][1], bfr[cb][ni], acc[1][ni]); }
;             __builtin_amdgcn_sched_barrier(0);
;         }
;         __builtin_amdgcn_s_setprio(0);
;         lds_barrier();
;         if (kc + 1 < nk) {
;             lstore();
;             if (kc + 2 < nk) gload(kc + 2);
;             lds_barrier();
;         }
.LBB0_115:
	s_cmp_gt_u32 s5, 14
	s_cbranch_scc1 .Lmy_gorig_5
	ds_read_b128 v[190:193], v187
	ds_read_b128 v[194:197], v187 offset:4608
	ds_read_b128 v[198:201], v188 offset:18432
	ds_read_b128 v[202:205], v188 offset:23040
	ds_read_b128 v[206:209], v188 offset:27648
	ds_read_b128 v[210:213], v188 offset:32256
	s_setprio 3
	ds_read_b128 v[214:217], v187 offset:32
	ds_read_b128 v[218:221], v187 offset:4640
	ds_read_b128 v[224:227], v188 offset:18464
	ds_read_b128 v[234:237], v188 offset:23072
	ds_read_b128 v[238:241], v188 offset:27680
	ds_read_b128 v[242:245], v188 offset:32288
	s_waitcnt lgkmcnt(9)
	v_mfma_f32_32x32x16_bf16 v[114:129], v[190:193], v[198:201], v[114:129]
	v_mfma_f32_32x32x16_bf16 v[98:113], v[194:197], v[198:201], v[98:113]
	s_waitcnt lgkmcnt(8)
	v_mfma_f32_32x32x16_bf16 v[82:97], v[190:193], v[202:205], v[82:97]
	v_mfma_f32_32x32x16_bf16 v[66:81], v[194:197], v[202:205], v[66:81]
	s_waitcnt lgkmcnt(7)
	v_mfma_f32_32x32x16_bf16 v[50:65], v[190:193], v[206:209], v[50:65]
	v_mfma_f32_32x32x16_bf16 v[34:49], v[194:197], v[206:209], v[34:49]
	s_waitcnt lgkmcnt(6)
	v_mfma_f32_32x32x16_bf16 v[18:33], v[190:193], v[210:213], v[18:33]
	v_mfma_f32_32x32x16_bf16 v[2:17], v[194:197], v[210:213], v[2:17]
	ds_read_b128 v[190:193], v187 offset:64
	ds_read_b128 v[194:197], v187 offset:4672
	ds_read_b128 v[198:201], v188 offset:18496
	ds_read_b128 v[202:205], v188 offset:23104
	ds_read_b128 v[206:209], v188 offset:27712
	ds_read_b128 v[210:213], v188 offset:32320
	s_waitcnt lgkmcnt(9)
	v_mfma_f32_32x32x16_bf16 v[114:129], v[214:217], v[224:227], v[114:129]
	v_mfma_f32_32x32x16_bf16 v[98:113], v[218:221], v[224:227], v[98:113]
	s_waitcnt lgkmcnt(8)
	v_mfma_f32_32x32x16_bf16 v[82:97], v[214:217], v[234:237], v[82:97]
	v_mfma_f32_32x32x16_bf16 v[66:81], v[218:221], v[234:237], v[66:81]
	s_waitcnt lgkmcnt(7)
	v_mfma_f32_32x32x16_bf16 v[50:65], v[214:217], v[238:241], v[50:65]
	v_mfma_f32_32x32x16_bf16 v[34:49], v[218:221], v[238:241], v[34:49]
	s_waitcnt lgkmcnt(6)
	v_mfma_f32_32x32x16_bf16 v[18:33], v[214:217], v[242:245], v[18:33]
	v_mfma_f32_32x32x16_bf16 v[2:17], v[218:221], v[242:245], v[2:17]
	ds_read_b128 v[214:217], v187 offset:96
	ds_read_b128 v[218:221], v187 offset:4704
	ds_read_b128 v[224:227], v188 offset:18528
	ds_read_b128 v[234:237], v188 offset:23136
	ds_read_b128 v[238:241], v188 offset:27744
	ds_read_b128 v[242:245], v188 offset:32352
	s_waitcnt lgkmcnt(9)
	v_mfma_f32_32x32x16_bf16 v[114:129], v[190:193], v[198:201], v[114:129]
	v_mfma_f32_32x32x16_bf16 v[98:113], v[194:197], v[198:201], v[98:113]
	s_waitcnt lgkmcnt(8)
	v_mfma_f32_32x32x16_bf16 v[82:97], v[190:193], v[202:205], v[82:97]
	v_mfma_f32_32x32x16_bf16 v[66:81], v[194:197], v[202:205], v[66:81]
	s_waitcnt lgkmcnt(0)
	s_barrier
	v_mfma_f32_32x32x16_bf16 v[50:65], v[190:193], v[206:209], v[50:65]
	s_waitcnt vmcnt(9)
	ds_write_b128 v189, v[130:133]
	v_mfma_f32_32x32x16_bf16 v[34:49], v[194:197], v[206:209], v[34:49]
	ds_write_b128 v189, v[134:137] offset:4608
	v_mfma_f32_32x32x16_bf16 v[18:33], v[190:193], v[210:213], v[18:33]
	ds_write_b128 v189, v[138:141] offset:9216
	v_mfma_f32_32x32x16_bf16 v[2:17], v[194:197], v[210:213], v[2:17]
	s_waitcnt vmcnt(7)
	ds_write_b128 v189, v[142:145] offset:13824
	v_mfma_f32_32x32x16_bf16 v[114:129], v[214:217], v[224:227], v[114:129]
	ds_write_b128 v189, v[146:149] offset:18432
	v_mfma_f32_32x32x16_bf16 v[98:113], v[218:221], v[224:227], v[98:113]
	s_waitcnt vmcnt(6)
	ds_write_b128 v189, v[150:153] offset:23040
	v_mfma_f32_32x32x16_bf16 v[82:97], v[214:217], v[234:237], v[82:97]
	s_waitcnt vmcnt(5)
	ds_write_b128 v189, v[154:157] offset:27648
	v_mfma_f32_32x32x16_bf16 v[66:81], v[218:221], v[234:237], v[66:81]
	s_waitcnt vmcnt(4)
	ds_write_b128 v189, v[158:161] offset:32256
	v_mfma_f32_32x32x16_bf16 v[50:65], v[214:217], v[238:241], v[50:65]
	s_waitcnt vmcnt(3)
	ds_write_b128 v189, v[162:165] offset:36864
	v_mfma_f32_32x32x16_bf16 v[34:49], v[218:221], v[238:241], v[34:49]
	s_waitcnt vmcnt(2)
	ds_write_b128 v189, v[166:169] offset:41472
	v_mfma_f32_32x32x16_bf16 v[18:33], v[214:217], v[242:245], v[18:33]
	s_waitcnt vmcnt(1)
	ds_write_b128 v189, v[170:173] offset:46080
	v_mfma_f32_32x32x16_bf16 v[2:17], v[218:221], v[242:245], v[2:17]
	s_waitcnt vmcnt(0)
	ds_write_b128 v189, v[174:177] offset:50688
	s_cmpk_eq_i32 s6, 0x700
	s_cbranch_scc1 .Lmy_gnold_5
	v_lshl_add_u64 v[138:139], v[184:185], 0, s[6:7]
	v_add_co_u32_e32 v130, vcc, 0x38a8000, v138
	v_lshl_add_u64 v[170:171], v[182:183], 0, s[6:7]
	s_nop 0
	v_addc_co_u32_e32 v131, vcc, 0, v139, vcc
	v_add_co_u32_e32 v134, vcc, 0x38b8000, v138
	s_nop 1
	v_addc_co_u32_e32 v135, vcc, 0, v139, vcc
	v_add_co_u32_e32 v140, vcc, 0x38c8000, v138
	global_load_dwordx4 v[130:133], v[130:131], off offset:256
	s_nop 0
	global_load_dwordx4 v[134:137], v[134:135], off offset:256
	v_addc_co_u32_e32 v141, vcc, 0, v139, vcc
	v_add_co_u32_e32 v142, vcc, 0x38d8000, v138
	s_nop 1
	v_addc_co_u32_e32 v143, vcc, 0, v139, vcc
	v_add_co_u32_e32 v146, vcc, 0x1c88000, v170
	global_load_dwordx4 v[138:141], v[140:141], off offset:256
	s_nop 0
	global_load_dwordx4 v[142:145], v[142:143], off offset:256
	v_addc_co_u32_e32 v147, vcc, 0, v171, vcc
	v_add_co_u32_e32 v150, vcc, 0x1c98000, v170
	s_nop 1
	v_addc_co_u32_e32 v151, vcc, 0, v171, vcc
	v_add_co_u32_e32 v154, vcc, 0x1ca8000, v170
	global_load_dwordx4 v[146:149], v[146:147], off offset:256
	s_nop 0
	global_load_dwordx4 v[150:153], v[150:151], off offset:256
	v_addc_co_u32_e32 v155, vcc, 0, v171, vcc
	v_add_co_u32_e32 v158, vcc, 0x1cb8000, v170
	s_nop 1
	v_addc_co_u32_e32 v159, vcc, 0, v171, vcc
	v_add_co_u32_e32 v162, vcc, 0x1cc8000, v170
	global_load_dwordx4 v[154:157], v[154:155], off offset:256
	s_nop 0
	global_load_dwordx4 v[158:161], v[158:159], off offset:256
	v_addc_co_u32_e32 v163, vcc, 0, v171, vcc
	v_add_co_u32_e32 v166, vcc, 0x1cd8000, v170
	s_nop 1
	v_addc_co_u32_e32 v167, vcc, 0, v171, vcc
	v_add_co_u32_e32 v172, vcc, 0x1ce8000, v170
	global_load_dwordx4 v[162:165], v[162:163], off offset:256
	s_nop 0
	global_load_dwordx4 v[166:169], v[166:167], off offset:256
	v_addc_co_u32_e32 v173, vcc, 0, v171, vcc
	v_add_co_u32_e32 v174, vcc, 0x1cf8000, v170
	s_nop 1
	v_addc_co_u32_e32 v175, vcc, 0, v171, vcc
	global_load_dwordx4 v[170:173], v[172:173], off offset:256
	s_nop 0
	global_load_dwordx4 v[174:177], v[174:175], off offset:256

; __device__ __forceinline__ void lds_barrier() { asm volatile("s_waitcnt lgkmcnt(0)\n\ts_barrier" ::: "memory"); }
; __device__ __forceinline__ f32x16 mfma32(bf16x8 a, bf16x8 b, f32x16 c) { return __builtin_amdgcn_mfma_f32_32x32x16_bf16(a, b, c, 0, 0, 0); }
; __device__ __forceinline__ void gemm_big(const bf16_t* __restrict__ A, long lda, const bf16_t* __restrict__ Bt, int K, f32x16 (&acc)[2][4], unsigned char* lds) {
;     ...
;     for (int kc = 0; kc < nk; ++kc) {
;         bf16x8 af[2][2], bfr[2][4];
;         af[0][0] = *(const bf16x8*)(Ac); af[0][1] = *(const bf16x8*)(Ac + 32 * GLD);
; #pragma unroll
;         for (int ni = 0; ni < 4; ++ni) bfr[0][ni] = *(const bf16x8*)(Bc + ni * 32 * GLD);
;         __builtin_amdgcn_s_setprio(3);
; #pragma unroll
;         for (int ks = 0; ks < 4; ++ks) {
;             const int cb = ks & 1, nb = cb ^ 1;
;             if (ks < 3) {
;                 af[nb][0] = *(const bf16x8*)(Ac + (ks + 1) * 16); af[nb][1] = *(const bf16x8*)(Ac + 32 * GLD + (ks + 1) * 16);
; #pragma unroll
;                 for (int ni = 0; ni < 4; ++ni) bfr[nb][ni] = *(const bf16x8*)(Bc + ni * 32 * GLD + (ks + 1) * 16);
;             }
;             __builtin_amdgcn_sched_barrier(0);
; #pragma unroll
;             for (int ni = 0; ni < 4; ++ni) { acc[0][ni] = mfma32(af[cb][0], bfr[cb][ni], acc[0][ni]); acc[1][ni] = mfma32(af[cb][1], bfr[cb][ni], acc[1][ni]); }
;             __builtin_amdgcn_sched_barrier(0);
;         }
;         __builtin_amdgcn_s_setprio(0);
;         lds_barrier();
;         if (kc + 1 < nk) {
;             lstore();
;             if (kc + 2 < nk) gload(kc + 2);
;             lds_barrier();
;         }
.LBB0_283:
	s_cmp_gt_u32 s5, 2
	s_cbranch_scc1 .Lmy_gorig_3
	ds_read_b128 v[192:195], v189
	ds_read_b128 v[196:199], v189 offset:4608
	ds_read_b128 v[200:203], v190 offset:18432
	ds_read_b128 v[204:207], v190 offset:23040
	ds_read_b128 v[208:211], v190 offset:27648
	ds_read_b128 v[212:215], v190 offset:32256
	s_setprio 3
	ds_read_b128 v[216:219], v189 offset:32
	ds_read_b128 v[224:227], v189 offset:4640
	ds_read_b128 v[234:237], v190 offset:18464
	ds_read_b128 v[238:241], v190 offset:23072
	ds_read_b128 v[242:245], v190 offset:27680
	ds_read_b128 v[246:249], v190 offset:32288
	s_waitcnt lgkmcnt(9)
	v_mfma_f32_32x32x16_bf16 v[114:129], v[192:195], v[200:203], v[114:129]
	v_mfma_f32_32x32x16_bf16 v[50:65], v[196:199], v[200:203], v[50:65]
	s_waitcnt lgkmcnt(8)
	v_mfma_f32_32x32x16_bf16 v[98:113], v[192:195], v[204:207], v[98:113]
	v_mfma_f32_32x32x16_bf16 v[34:49], v[196:199], v[204:207], v[34:49]
	s_waitcnt lgkmcnt(7)
	v_mfma_f32_32x32x16_bf16 v[82:97], v[192:195], v[208:211], v[82:97]
	v_mfma_f32_32x32x16_bf16 v[18:33], v[196:199], v[208:211], v[18:33]
	s_waitcnt lgkmcnt(6)
	v_mfma_f32_32x32x16_bf16 v[66:81], v[192:195], v[212:215], v[66:81]
	v_mfma_f32_32x32x16_bf16 v[2:17], v[196:199], v[212:215], v[2:17]
	ds_read_b128 v[192:195], v189 offset:64
	ds_read_b128 v[196:199], v189 offset:4672
	ds_read_b128 v[200:203], v190 offset:18496
	ds_read_b128 v[204:207], v190 offset:23104
	ds_read_b128 v[208:211], v190 offset:27712
	ds_read_b128 v[212:215], v190 offset:32320
	s_waitcnt lgkmcnt(9)
	v_mfma_f32_32x32x16_bf16 v[114:129], v[216:219], v[234:237], v[114:129]
	v_mfma_f32_32x32x16_bf16 v[50:65], v[224:227], v[234:237], v[50:65]
	s_waitcnt lgkmcnt(8)
	v_mfma_f32_32x32x16_bf16 v[98:113], v[216:219], v[238:241], v[98:113]
	v_mfma_f32_32x32x16_bf16 v[34:49], v[224:227], v[238:241], v[34:49]
	s_waitcnt lgkmcnt(7)
	v_mfma_f32_32x32x16_bf16 v[82:97], v[216:219], v[242:245], v[82:97]
	v_mfma_f32_32x32x16_bf16 v[18:33], v[224:227], v[242:245], v[18:33]
	s_waitcnt lgkmcnt(6)
	v_mfma_f32_32x32x16_bf16 v[66:81], v[216:219], v[246:249], v[66:81]
	v_mfma_f32_32x32x16_bf16 v[2:17], v[224:227], v[246:249], v[2:17]
	ds_read_b128 v[216:219], v189 offset:96
	ds_read_b128 v[224:227], v189 offset:4704
	ds_read_b128 v[234:237], v190 offset:18528
	ds_read_b128 v[238:241], v190 offset:23136
	ds_read_b128 v[242:245], v190 offset:27744
	ds_read_b128 v[246:249], v190 offset:32352
	s_waitcnt lgkmcnt(9)
	v_mfma_f32_32x32x16_bf16 v[114:129], v[192:195], v[200:203], v[114:129]
	v_mfma_f32_32x32x16_bf16 v[50:65], v[196:199], v[200:203], v[50:65]
	s_waitcnt lgkmcnt(8)
	v_mfma_f32_32x32x16_bf16 v[98:113], v[192:195], v[204:207], v[98:113]
	v_mfma_f32_32x32x16_bf16 v[34:49], v[196:199], v[204:207], v[34:49]
	s_waitcnt lgkmcnt(0)
	s_barrier
	v_mfma_f32_32x32x16_bf16 v[82:97], v[192:195], v[208:211], v[82:97]
	s_waitcnt vmcnt(9)
	ds_write_b128 v191, v[130:133]
	v_mfma_f32_32x32x16_bf16 v[18:33], v[196:199], v[208:211], v[18:33]
	ds_write_b128 v191, v[134:137] offset:4608
	v_mfma_f32_32x32x16_bf16 v[66:81], v[192:195], v[212:215], v[66:81]
	ds_write_b128 v191, v[138:141] offset:9216
	v_mfma_f32_32x32x16_bf16 v[2:17], v[196:199], v[212:215], v[2:17]
	s_waitcnt vmcnt(7)
	ds_write_b128 v191, v[142:145] offset:13824
	v_mfma_f32_32x32x16_bf16 v[114:129], v[216:219], v[234:237], v[114:129]
	ds_write_b128 v191, v[146:149] offset:18432
	v_mfma_f32_32x32x16_bf16 v[50:65], v[224:227], v[234:237], v[50:65]
	s_waitcnt vmcnt(6)
	ds_write_b128 v191, v[150:153] offset:23040
	v_mfma_f32_32x32x16_bf16 v[98:113], v[216:219], v[238:241], v[98:113]
	s_waitcnt vmcnt(5)
	ds_write_b128 v191, v[154:157] offset:27648
	v_mfma_f32_32x32x16_bf16 v[34:49], v[224:227], v[238:241], v[34:49]
	s_waitcnt vmcnt(4)
	ds_write_b128 v191, v[158:161] offset:32256
	v_mfma_f32_32x32x16_bf16 v[82:97], v[216:219], v[242:245], v[82:97]
	s_waitcnt vmcnt(3)
	ds_write_b128 v191, v[162:165] offset:36864
	v_mfma_f32_32x32x16_bf16 v[18:33], v[224:227], v[242:245], v[18:33]
	s_waitcnt vmcnt(2)
	ds_write_b128 v191, v[166:169] offset:41472
	v_mfma_f32_32x32x16_bf16 v[66:81], v[216:219], v[246:249], v[66:81]
	s_waitcnt vmcnt(1)
	ds_write_b128 v191, v[170:173] offset:46080
	v_mfma_f32_32x32x16_bf16 v[2:17], v[224:227], v[246:249], v[2:17]
	s_waitcnt vmcnt(0)
	ds_write_b128 v191, v[174:177] offset:50688
	s_cmpk_eq_i32 s6, 0x100
	s_cbranch_scc1 .Lmy_gnold_3
	v_lshl_add_u64 v[138:139], v[184:185], 0, s[6:7]
	v_add_co_u32_e32 v130, vcc, 0x78a8000, v138
	v_lshl_add_u64 v[170:171], v[182:183], 0, s[6:7]
	s_nop 0
	v_addc_co_u32_e32 v131, vcc, 0, v139, vcc
	v_add_co_u32_e32 v134, vcc, 0x78e6000, v138
	s_nop 1
	v_addc_co_u32_e32 v135, vcc, 0, v139, vcc
	v_add_co_u32_e32 v140, vcc, 0x7924000, v138
	global_load_dwordx4 v[130:133], v[130:131], off offset:3328
	s_nop 0
	global_load_dwordx4 v[134:137], v[134:135], off offset:3328
	v_addc_co_u32_e32 v141, vcc, 0, v139, vcc
	v_add_co_u32_e32 v142, vcc, 0x7962000, v138
	s_nop 1
	v_addc_co_u32_e32 v143, vcc, 0, v139, vcc
	v_add_co_u32_e32 v146, vcc, 0x2288000, v170
	global_load_dwordx4 v[138:141], v[140:141], off offset:3328
	s_nop 0
	global_load_dwordx4 v[142:145], v[142:143], off offset:3328
	v_addc_co_u32_e32 v147, vcc, 0, v171, vcc
	v_add_co_u32_e32 v150, vcc, 0x228c000, v170
	s_nop 1
	v_addc_co_u32_e32 v151, vcc, 0, v171, vcc
	v_add_co_u32_e32 v154, vcc, 0x2290000, v170
	global_load_dwordx4 v[146:149], v[146:147], off offset:256
	s_nop 0
	global_load_dwordx4 v[150:153], v[150:151], off offset:256
	v_addc_co_u32_e32 v155, vcc, 0, v171, vcc
	v_add_co_u32_e32 v158, vcc, 0x2294000, v170
	s_nop 1
	v_addc_co_u32_e32 v159, vcc, 0, v171, vcc
	v_add_co_u32_e32 v162, vcc, 0x2298000, v170
	global_load_dwordx4 v[154:157], v[154:155], off offset:256
	s_nop 0
	global_load_dwordx4 v[158:161], v[158:159], off offset:256
	v_addc_co_u32_e32 v163, vcc, 0, v171, vcc
	v_add_co_u32_e32 v166, vcc, 0x229c000, v170
	s_nop 1
	v_addc_co_u32_e32 v167, vcc, 0, v171, vcc
	v_add_co_u32_e32 v172, vcc, 0x22a0000, v170
	global_load_dwordx4 v[162:165], v[162:163], off offset:256
	s_nop 0
	global_load_dwordx4 v[166:169], v[166:167], off offset:256
	v_addc_co_u32_e32 v173, vcc, 0, v171, vcc
	v_add_co_u32_e32 v174, vcc, 0x22a4000, v170
	s_nop 1
	v_addc_co_u32_e32 v175, vcc, 0, v171, vcc
	global_load_dwordx4 v[170:173], v[172:173], off offset:256
	s_nop 0
	global_load_dwordx4 v[174:177], v[174:175], off offset:256

; __device__ __forceinline__ void lds_barrier() { asm volatile("s_waitcnt lgkmcnt(0)\n\ts_barrier" ::: "memory"); }
; __device__ __forceinline__ f32x16 mfma32(bf16x8 a, bf16x8 b, f32x16 c) { return __builtin_amdgcn_mfma_f32_32x32x16_bf16(a, b, c, 0, 0, 0); }
; __device__ __forceinline__ void gemm_big(const bf16_t* __restrict__ A, long lda, const bf16_t* __restrict__ Bt, int K, f32x16 (&acc)[2][4], unsigned char* lds) {
;     ...
;     for (int kc = 0; kc < nk; ++kc) {
;         bf16x8 af[2][2], bfr[2][4];
;         af[0][0] = *(const bf16x8*)(Ac); af[0][1] = *(const bf16x8*)(Ac + 32 * GLD);
; #pragma unroll
;         for (int ni = 0; ni < 4; ++ni) bfr[0][ni] = *(const bf16x8*)(Bc + ni * 32 * GLD);
;         __builtin_amdgcn_s_setprio(3);
; #pragma unroll
;         for (int ks = 0; ks < 4; ++ks) {
;             const int cb = ks & 1, nb = cb ^ 1;
;             if (ks < 3) {
;                 af[nb][0] = *(const bf16x8*)(Ac + (ks + 1) * 16); af[nb][1] = *(const bf16x8*)(Ac + 32 * GLD + (ks + 1) * 16);
; #pragma unroll
;                 for (int ni = 0; ni < 4; ++ni) bfr[nb][ni] = *(const bf16x8*)(Bc + ni * 32 * GLD + (ks + 1) * 16);
;             }
;             __builtin_amdgcn_sched_barrier(0);
; #pragma unroll
;             for (int ni = 0; ni < 4; ++ni) { acc[0][ni] = mfma32(af[cb][0], bfr[cb][ni], acc[0][ni]); acc[1][ni] = mfma32(af[cb][1], bfr[cb][ni], acc[1][ni]); }
;             __builtin_amdgcn_sched_barrier(0);
;         }
;         __builtin_amdgcn_s_setprio(0);
;         lds_barrier();
;         if (kc + 1 < nk) {
;             lstore();
;             if (kc + 2 < nk) gload(kc + 2);
;             lds_barrier();
;         }
.LBB0_678:
	s_cmp_gt_u32 s6, 14
	s_cbranch_scc1 .Lmy_gorig_2
	ds_read_b128 v[192:195], v189
	ds_read_b128 v[196:199], v189 offset:4608
	ds_read_b128 v[200:203], v190 offset:18432
	ds_read_b128 v[204:207], v190 offset:23040
	ds_read_b128 v[208:211], v190 offset:27648
	ds_read_b128 v[212:215], v190 offset:32256
	s_setprio 3
	ds_read_b128 v[216:219], v189 offset:32
	ds_read_b128 v[234:237], v189 offset:4640
	ds_read_b128 v[238:241], v190 offset:18464
	ds_read_b128 v[242:245], v190 offset:23072
	ds_read_b128 v[246:249], v190 offset:27680
	ds_read_b128 v[224:227], v190 offset:32288
	s_waitcnt lgkmcnt(9)
	v_mfma_f32_32x32x16_bf16 v[114:129], v[192:195], v[200:203], v[114:129]
	v_mfma_f32_32x32x16_bf16 v[98:113], v[196:199], v[200:203], v[98:113]
	s_waitcnt lgkmcnt(8)
	v_mfma_f32_32x32x16_bf16 v[82:97], v[192:195], v[204:207], v[82:97]
	v_mfma_f32_32x32x16_bf16 v[66:81], v[196:199], v[204:207], v[66:81]
	s_waitcnt lgkmcnt(7)
	v_mfma_f32_32x32x16_bf16 v[50:65], v[192:195], v[208:211], v[50:65]
	v_mfma_f32_32x32x16_bf16 v[34:49], v[196:199], v[208:211], v[34:49]
	s_waitcnt lgkmcnt(6)
	v_mfma_f32_32x32x16_bf16 v[18:33], v[192:195], v[212:215], v[18:33]
	v_mfma_f32_32x32x16_bf16 v[2:17], v[196:199], v[212:215], v[2:17]
	ds_read_b128 v[192:195], v189 offset:64
	ds_read_b128 v[196:199], v189 offset:4672
	ds_read_b128 v[200:203], v190 offset:18496
	ds_read_b128 v[204:207], v190 offset:23104
	ds_read_b128 v[208:211], v190 offset:27712
	ds_read_b128 v[212:215], v190 offset:32320
	s_waitcnt lgkmcnt(9)
	v_mfma_f32_32x32x16_bf16 v[114:129], v[216:219], v[238:241], v[114:129]
	v_mfma_f32_32x32x16_bf16 v[98:113], v[234:237], v[238:241], v[98:113]
	s_waitcnt lgkmcnt(8)
	v_mfma_f32_32x32x16_bf16 v[82:97], v[216:219], v[242:245], v[82:97]
	v_mfma_f32_32x32x16_bf16 v[66:81], v[234:237], v[242:245], v[66:81]
	s_waitcnt lgkmcnt(7)
	v_mfma_f32_32x32x16_bf16 v[50:65], v[216:219], v[246:249], v[50:65]
	v_mfma_f32_32x32x16_bf16 v[34:49], v[234:237], v[246:249], v[34:49]
	s_waitcnt lgkmcnt(6)
	v_mfma_f32_32x32x16_bf16 v[18:33], v[216:219], v[224:227], v[18:33]
	v_mfma_f32_32x32x16_bf16 v[2:17], v[234:237], v[224:227], v[2:17]
	ds_read_b128 v[216:219], v189 offset:96
	ds_read_b128 v[224:227], v189 offset:4704
	ds_read_b128 v[234:237], v190 offset:18528
	ds_read_b128 v[238:241], v190 offset:23136
	ds_read_b128 v[242:245], v190 offset:27744
	ds_read_b128 v[246:249], v190 offset:32352
	s_waitcnt lgkmcnt(9)
	v_mfma_f32_32x32x16_bf16 v[114:129], v[192:195], v[200:203], v[114:129]
	v_mfma_f32_32x32x16_bf16 v[98:113], v[196:199], v[200:203], v[98:113]
	s_waitcnt lgkmcnt(8)
	v_mfma_f32_32x32x16_bf16 v[82:97], v[192:195], v[204:207], v[82:97]
	v_mfma_f32_32x32x16_bf16 v[66:81], v[196:199], v[204:207], v[66:81]
	s_waitcnt lgkmcnt(0)
	s_barrier
	v_mfma_f32_32x32x16_bf16 v[50:65], v[192:195], v[208:211], v[50:65]
	s_waitcnt vmcnt(9)
	ds_write_b128 v188, v[130:133]
	v_mfma_f32_32x32x16_bf16 v[34:49], v[196:199], v[208:211], v[34:49]
	ds_write_b128 v188, v[134:137] offset:4608
	v_mfma_f32_32x32x16_bf16 v[18:33], v[192:195], v[212:215], v[18:33]
	ds_write_b128 v188, v[138:141] offset:9216
	v_mfma_f32_32x32x16_bf16 v[2:17], v[196:199], v[212:215], v[2:17]
	s_waitcnt vmcnt(7)
	ds_write_b128 v188, v[142:145] offset:13824
	v_mfma_f32_32x32x16_bf16 v[114:129], v[216:219], v[234:237], v[114:129]
	ds_write_b128 v188, v[146:149] offset:18432
	v_mfma_f32_32x32x16_bf16 v[98:113], v[224:227], v[234:237], v[98:113]
	s_waitcnt vmcnt(6)
	ds_write_b128 v188, v[150:153] offset:23040
	v_mfma_f32_32x32x16_bf16 v[82:97], v[216:219], v[238:241], v[82:97]
	s_waitcnt vmcnt(5)
	ds_write_b128 v188, v[154:157] offset:27648
	v_mfma_f32_32x32x16_bf16 v[66:81], v[224:227], v[238:241], v[66:81]
	s_waitcnt vmcnt(4)
	ds_write_b128 v188, v[158:161] offset:32256
	v_mfma_f32_32x32x16_bf16 v[50:65], v[216:219], v[242:245], v[50:65]
	s_waitcnt vmcnt(3)
	ds_write_b128 v188, v[162:165] offset:36864
	v_mfma_f32_32x32x16_bf16 v[34:49], v[224:227], v[242:245], v[34:49]
	s_waitcnt vmcnt(2)
	ds_write_b128 v188, v[166:169] offset:41472
	v_mfma_f32_32x32x16_bf16 v[18:33], v[216:219], v[246:249], v[18:33]
	s_waitcnt vmcnt(1)
	ds_write_b128 v188, v[170:173] offset:46080
	v_mfma_f32_32x32x16_bf16 v[2:17], v[224:227], v[246:249], v[2:17]
	s_waitcnt vmcnt(0)
	ds_write_b128 v188, v[174:177] offset:50688
	s_cmpk_eq_i32 s0, 0x700
	s_cbranch_scc1 .Lmy_gnold_2
	v_lshl_add_u64 v[138:139], v[184:185], 0, s[0:1]
	v_add_co_u32_e32 v130, vcc, 0x38a8000, v138
	v_lshl_add_u64 v[170:171], v[182:183], 0, s[0:1]
	s_nop 0
	v_addc_co_u32_e32 v131, vcc, 0, v139, vcc
	v_add_co_u32_e32 v134, vcc, 0x38b8000, v138
	s_nop 1
	v_addc_co_u32_e32 v135, vcc, 0, v139, vcc
	v_add_co_u32_e32 v140, vcc, 0x38c8000, v138
	global_load_dwordx4 v[130:133], v[130:131], off offset:256
	s_nop 0
	global_load_dwordx4 v[134:137], v[134:135], off offset:256
	v_addc_co_u32_e32 v141, vcc, 0, v139, vcc
	v_add_co_u32_e32 v142, vcc, 0x38d8000, v138
	s_nop 1
	v_addc_co_u32_e32 v143, vcc, 0, v139, vcc
	v_add_co_u32_e32 v146, vcc, 0x1488000, v170
	global_load_dwordx4 v[138:141], v[140:141], off offset:256
	s_nop 0
	global_load_dwordx4 v[142:145], v[142:143], off offset:256
	v_addc_co_u32_e32 v147, vcc, 0, v171, vcc
	v_add_co_u32_e32 v150, vcc, 0x1498000, v170
	s_nop 1
	v_addc_co_u32_e32 v151, vcc, 0, v171, vcc
	v_add_co_u32_e32 v154, vcc, 0x14a8000, v170
	global_load_dwordx4 v[146:149], v[146:147], off offset:256
	s_nop 0
	global_load_dwordx4 v[150:153], v[150:151], off offset:256
	v_addc_co_u32_e32 v155, vcc, 0, v171, vcc
	v_add_co_u32_e32 v158, vcc, 0x14b8000, v170
	s_nop 1
	v_addc_co_u32_e32 v159, vcc, 0, v171, vcc
	v_add_co_u32_e32 v162, vcc, 0x14c8000, v170
	global_load_dwordx4 v[154:157], v[154:155], off offset:256
	s_nop 0
	global_load_dwordx4 v[158:161], v[158:159], off offset:256
	v_addc_co_u32_e32 v163, vcc, 0, v171, vcc
	v_add_co_u32_e32 v166, vcc, 0x14d8000, v170
	s_nop 1
	v_addc_co_u32_e32 v167, vcc, 0, v171, vcc
	v_add_co_u32_e32 v172, vcc, 0x14e8000, v170
	global_load_dwordx4 v[162:165], v[162:163], off offset:256
	s_nop 0
	global_load_dwordx4 v[166:169], v[166:167], off offset:256
	v_addc_co_u32_e32 v173, vcc, 0, v171, vcc
	v_add_co_u32_e32 v174, vcc, 0x14f8000, v170
	s_nop 1
	v_addc_co_u32_e32 v175, vcc, 0, v171, vcc
	global_load_dwordx4 v[170:173], v[172:173], off offset:256
	s_nop 0
	global_load_dwordx4 v[174:177], v[174:175], off offset:256

; __device__ __forceinline__ void lds_barrier() { asm volatile("s_waitcnt lgkmcnt(0)\n\ts_barrier" ::: "memory"); }
; __device__ __forceinline__ f32x16 mfma32(bf16x8 a, bf16x8 b, f32x16 c) { return __builtin_amdgcn_mfma_f32_32x32x16_bf16(a, b, c, 0, 0, 0); }
; __device__ __forceinline__ void gemm_big(const bf16_t* __restrict__ A, long lda, const bf16_t* __restrict__ Bt, int K, f32x16 (&acc)[2][4], unsigned char* lds) {
;     ...
;     for (int kc = 0; kc < nk; ++kc) {
;         bf16x8 af[2][2], bfr[2][4];
;         af[0][0] = *(const bf16x8*)(Ac); af[0][1] = *(const bf16x8*)(Ac + 32 * GLD);
; #pragma unroll
;         for (int ni = 0; ni < 4; ++ni) bfr[0][ni] = *(const bf16x8*)(Bc + ni * 32 * GLD);
;         __builtin_amdgcn_s_setprio(3);
; #pragma unroll
;         for (int ks = 0; ks < 4; ++ks) {
;             const int cb = ks & 1, nb = cb ^ 1;
;             if (ks < 3) {
;                 af[nb][0] = *(const bf16x8*)(Ac + (ks + 1) * 16); af[nb][1] = *(const bf16x8*)(Ac + 32 * GLD + (ks + 1) * 16);
; #pragma unroll
;                 for (int ni = 0; ni < 4; ++ni) bfr[nb][ni] = *(const bf16x8*)(Bc + ni * 32 * GLD + (ks + 1) * 16);
;             }
;             __builtin_amdgcn_sched_barrier(0);
; #pragma unroll
;             for (int ni = 0; ni < 4; ++ni) { acc[0][ni] = mfma32(af[cb][0], bfr[cb][ni], acc[0][ni]); acc[1][ni] = mfma32(af[cb][1], bfr[cb][ni], acc[1][ni]); }
;             __builtin_amdgcn_sched_barrier(0);
;         }
;         __builtin_amdgcn_s_setprio(0);
;         lds_barrier();
;         if (kc + 1 < nk) {
;             lstore();
;             if (kc + 2 < nk) gload(kc + 2);
;             lds_barrier();
;         }
.LBB0_775:
	s_cmp_gt_u32 s14, 42
	s_cbranch_scc1 .Lmy_gorig_1
	ds_read_b128 v[190:193], v187
	ds_read_b128 v[194:197], v187 offset:4608
	ds_read_b128 v[198:201], v188 offset:18432
	ds_read_b128 v[202:205], v188 offset:23040
	ds_read_b128 v[206:209], v188 offset:27648
	ds_read_b128 v[210:213], v188 offset:32256
	s_setprio 3
	ds_read_b128 v[214:217], v187 offset:32
	ds_read_b128 v[218:221], v187 offset:4640
	ds_read_b128 v[234:237], v188 offset:18464
	ds_read_b128 v[238:241], v188 offset:23072
	ds_read_b128 v[242:245], v188 offset:27680
	ds_read_b128 v[246:249], v188 offset:32288
	s_waitcnt lgkmcnt(9)
	v_mfma_f32_32x32x16_bf16 v[114:129], v[190:193], v[198:201], v[114:129]
	v_mfma_f32_32x32x16_bf16 v[50:65], v[194:197], v[198:201], v[50:65]
	s_waitcnt lgkmcnt(8)
	v_mfma_f32_32x32x16_bf16 v[98:113], v[190:193], v[202:205], v[98:113]
	v_mfma_f32_32x32x16_bf16 v[34:49], v[194:197], v[202:205], v[34:49]
	s_waitcnt lgkmcnt(7)
	v_mfma_f32_32x32x16_bf16 v[82:97], v[190:193], v[206:209], v[82:97]
	v_mfma_f32_32x32x16_bf16 v[18:33], v[194:197], v[206:209], v[18:33]
	s_waitcnt lgkmcnt(6)
	v_mfma_f32_32x32x16_bf16 v[66:81], v[190:193], v[210:213], v[66:81]
	v_mfma_f32_32x32x16_bf16 v[2:17], v[194:197], v[210:213], v[2:17]
	ds_read_b128 v[190:193], v187 offset:64
	ds_read_b128 v[194:197], v187 offset:4672
	ds_read_b128 v[198:201], v188 offset:18496
	ds_read_b128 v[202:205], v188 offset:23104
	ds_read_b128 v[206:209], v188 offset:27712
	ds_read_b128 v[210:213], v188 offset:32320
	s_waitcnt lgkmcnt(9)
	v_mfma_f32_32x32x16_bf16 v[114:129], v[214:217], v[234:237], v[114:129]
	v_mfma_f32_32x32x16_bf16 v[50:65], v[218:221], v[234:237], v[50:65]
	s_waitcnt lgkmcnt(8)
	v_mfma_f32_32x32x16_bf16 v[98:113], v[214:217], v[238:241], v[98:113]
	v_mfma_f32_32x32x16_bf16 v[34:49], v[218:221], v[238:241], v[34:49]
	s_waitcnt lgkmcnt(7)
	v_mfma_f32_32x32x16_bf16 v[82:97], v[214:217], v[242:245], v[82:97]
	v_mfma_f32_32x32x16_bf16 v[18:33], v[218:221], v[242:245], v[18:33]
	s_waitcnt lgkmcnt(6)
	v_mfma_f32_32x32x16_bf16 v[66:81], v[214:217], v[246:249], v[66:81]
	v_mfma_f32_32x32x16_bf16 v[2:17], v[218:221], v[246:249], v[2:17]
	ds_read_b128 v[214:217], v187 offset:96
	ds_read_b128 v[218:221], v187 offset:4704
	ds_read_b128 v[234:237], v188 offset:18528
	ds_read_b128 v[238:241], v188 offset:23136
	ds_read_b128 v[242:245], v188 offset:27744
	ds_read_b128 v[246:249], v188 offset:32352
	s_waitcnt lgkmcnt(9)
	v_mfma_f32_32x32x16_bf16 v[114:129], v[190:193], v[198:201], v[114:129]
	v_mfma_f32_32x32x16_bf16 v[50:65], v[194:197], v[198:201], v[50:65]
	s_waitcnt lgkmcnt(8)
	v_mfma_f32_32x32x16_bf16 v[98:113], v[190:193], v[202:205], v[98:113]
	v_mfma_f32_32x32x16_bf16 v[34:49], v[194:197], v[202:205], v[34:49]
	s_waitcnt lgkmcnt(0)
	s_barrier
	v_mfma_f32_32x32x16_bf16 v[82:97], v[190:193], v[206:209], v[82:97]
	s_waitcnt vmcnt(9)
	ds_write_b128 v189, v[130:133]
	v_mfma_f32_32x32x16_bf16 v[18:33], v[194:197], v[206:209], v[18:33]
	ds_write_b128 v189, v[134:137] offset:4608
	v_mfma_f32_32x32x16_bf16 v[66:81], v[190:193], v[210:213], v[66:81]
	ds_write_b128 v189, v[138:141] offset:9216
	v_mfma_f32_32x32x16_bf16 v[2:17], v[194:197], v[210:213], v[2:17]
	s_waitcnt vmcnt(7)
	ds_write_b128 v189, v[142:145] offset:13824
	v_mfma_f32_32x32x16_bf16 v[114:129], v[214:217], v[234:237], v[114:129]
	ds_write_b128 v189, v[146:149] offset:18432
	v_mfma_f32_32x32x16_bf16 v[50:65], v[218:221], v[234:237], v[50:65]
	s_waitcnt vmcnt(6)
	ds_write_b128 v189, v[150:153] offset:23040
	v_mfma_f32_32x32x16_bf16 v[98:113], v[214:217], v[238:241], v[98:113]
	s_waitcnt vmcnt(5)
	ds_write_b128 v189, v[154:157] offset:27648
	v_mfma_f32_32x32x16_bf16 v[34:49], v[218:221], v[238:241], v[34:49]
	s_waitcnt vmcnt(4)
	ds_write_b128 v189, v[158:161] offset:32256
	v_mfma_f32_32x32x16_bf16 v[82:97], v[214:217], v[242:245], v[82:97]
	s_waitcnt vmcnt(3)
	ds_write_b128 v189, v[162:165] offset:36864
	v_mfma_f32_32x32x16_bf16 v[18:33], v[218:221], v[242:245], v[18:33]
	s_waitcnt vmcnt(2)
	ds_write_b128 v189, v[166:169] offset:41472
	v_mfma_f32_32x32x16_bf16 v[66:81], v[214:217], v[246:249], v[66:81]
	s_waitcnt vmcnt(1)
	ds_write_b128 v189, v[170:173] offset:46080
	v_mfma_f32_32x32x16_bf16 v[2:17], v[218:221], v[246:249], v[2:17]
	s_waitcnt vmcnt(0)
	ds_write_b128 v189, v[174:177] offset:50688
	s_cmpk_eq_i32 s4, 0x1500
	s_cbranch_scc1 .Lmy_gnold_1
	v_lshl_add_u64 v[138:139], v[184:185], 0, s[4:5]
	v_add_co_u32_e32 v130, vcc, 0x78a8000, v138
	v_lshl_add_u64 v[170:171], v[182:183], 0, s[4:5]
	s_nop 0
	v_addc_co_u32_e32 v131, vcc, 0, v139, vcc
	v_add_co_u32_e32 v134, vcc, 0x78d4000, v138
	s_nop 1
	v_addc_co_u32_e32 v135, vcc, 0, v139, vcc
	v_add_co_u32_e32 v140, vcc, 0x7900000, v138
	global_load_dwordx4 v[130:133], v[130:131], off offset:256
	s_nop 0
	global_load_dwordx4 v[134:137], v[134:135], off offset:256
	v_addc_co_u32_e32 v141, vcc, 0, v139, vcc
	v_add_co_u32_e32 v142, vcc, 0x792c000, v138
	s_nop 1
	v_addc_co_u32_e32 v143, vcc, 0, v139, vcc
	v_add_co_u32_e32 v146, vcc, 0xf08000, v170
	global_load_dwordx4 v[138:141], v[140:141], off offset:256
	s_nop 0
	global_load_dwordx4 v[142:145], v[142:143], off offset:256
	v_addc_co_u32_e32 v147, vcc, 0, v171, vcc
	v_add_co_u32_e32 v150, vcc, 0xf34000, v170
	s_nop 1
	v_addc_co_u32_e32 v151, vcc, 0, v171, vcc
	v_add_co_u32_e32 v154, vcc, 0xf60000, v170
	global_load_dwordx4 v[146:149], v[146:147], off offset:256
	s_nop 0
	global_load_dwordx4 v[150:153], v[150:151], off offset:256
	v_addc_co_u32_e32 v155, vcc, 0, v171, vcc
	v_add_co_u32_e32 v158, vcc, 0xf8c000, v170
	s_nop 1
	v_addc_co_u32_e32 v159, vcc, 0, v171, vcc
	v_add_co_u32_e32 v162, vcc, 0xfb8000, v170
	global_load_dwordx4 v[154:157], v[154:155], off offset:256
	s_nop 0
	global_load_dwordx4 v[158:161], v[158:159], off offset:256
	v_addc_co_u32_e32 v163, vcc, 0, v171, vcc
	v_add_co_u32_e32 v166, vcc, 0xfe4000, v170
	s_nop 1
	v_addc_co_u32_e32 v167, vcc, 0, v171, vcc
	v_add_co_u32_e32 v172, vcc, 0x1010000, v170
	global_load_dwordx4 v[162:165], v[162:163], off offset:256
	s_nop 0
	global_load_dwordx4 v[166:169], v[166:167], off offset:256
	v_addc_co_u32_e32 v173, vcc, 0, v171, vcc
	v_add_co_u32_e32 v174, vcc, 0x103c000, v170
	s_nop 1
	v_addc_co_u32_e32 v175, vcc, 0, v171, vcc
	global_load_dwordx4 v[170:173], v[172:173], off offset:256
	s_nop 0
	global_load_dwordx4 v[174:177], v[174:175], off offset:256

; __device__ __forceinline__ void lds_barrier() { asm volatile("s_waitcnt lgkmcnt(0)\n\ts_barrier" ::: "memory"); }
; __device__ __forceinline__ f32x16 mfma32(bf16x8 a, bf16x8 b, f32x16 c) { return __builtin_amdgcn_mfma_f32_32x32x16_bf16(a, b, c, 0, 0, 0); }
; __device__ __forceinline__ void gemm_big(const bf16_t* __restrict__ A, long lda, const bf16_t* __restrict__ Bt, int K, f32x16 (&acc)[2][4], unsigned char* lds) {
;     ...
;     for (int kc = 0; kc < nk; ++kc) {
;         bf16x8 af[2][2], bfr[2][4];
;         af[0][0] = *(const bf16x8*)(Ac); af[0][1] = *(const bf16x8*)(Ac + 32 * GLD);
; #pragma unroll
;         for (int ni = 0; ni < 4; ++ni) bfr[0][ni] = *(const bf16x8*)(Bc + ni * 32 * GLD);
;         __builtin_amdgcn_s_setprio(3);
; #pragma unroll
;         for (int ks = 0; ks < 4; ++ks) {
;             const int cb = ks & 1, nb = cb ^ 1;
;             if (ks < 3) {
;                 af[nb][0] = *(const bf16x8*)(Ac + (ks + 1) * 16); af[nb][1] = *(const bf16x8*)(Ac + 32 * GLD + (ks + 1) * 16);
; #pragma unroll
;                 for (int ni = 0; ni < 4; ++ni) bfr[nb][ni] = *(const bf16x8*)(Bc + ni * 32 * GLD + (ks + 1) * 16);
;             }
;             __builtin_amdgcn_sched_barrier(0);
; #pragma unroll
;             for (int ni = 0; ni < 4; ++ni) { acc[0][ni] = mfma32(af[cb][0], bfr[cb][ni], acc[0][ni]); acc[1][ni] = mfma32(af[cb][1], bfr[cb][ni], acc[1][ni]); }
;             __builtin_amdgcn_sched_barrier(0);
;         }
;         __builtin_amdgcn_s_setprio(0);
;         lds_barrier();
;         if (kc + 1 < nk) {
;             lstore();
;             if (kc + 2 < nk) gload(kc + 2);
;             lds_barrier();
;         }
.LBB0_788:
	s_cmp_gt_u32 s5, 14
	s_cbranch_scc1 .Lmy_gorig_0
	ds_read_b128 v[190:193], v188
	ds_read_b128 v[194:197], v188 offset:4608
	ds_read_b128 v[198:201], v189 offset:18432
	ds_read_b128 v[202:205], v189 offset:23040
	ds_read_b128 v[206:209], v189 offset:27648
	ds_read_b128 v[210:213], v189 offset:32256
	s_setprio 3
	ds_read_b128 v[214:217], v188 offset:32
	ds_read_b128 v[234:237], v188 offset:4640
	ds_read_b128 v[238:241], v189 offset:18464
	ds_read_b128 v[242:245], v189 offset:23072
	ds_read_b128 v[246:249], v189 offset:27680
	ds_read_b128 v[218:221], v189 offset:32288
	s_waitcnt lgkmcnt(9)
	v_mfma_f32_32x32x16_bf16 v[114:129], v[190:193], v[198:201], v[114:129]
	v_mfma_f32_32x32x16_bf16 v[82:97], v[194:197], v[198:201], v[82:97]
	s_waitcnt lgkmcnt(8)
	v_mfma_f32_32x32x16_bf16 v[98:113], v[190:193], v[202:205], v[98:113]
	v_mfma_f32_32x32x16_bf16 v[66:81], v[194:197], v[202:205], v[66:81]
	s_waitcnt lgkmcnt(7)
	v_mfma_f32_32x32x16_bf16 v[50:65], v[190:193], v[206:209], v[50:65]
	v_mfma_f32_32x32x16_bf16 v[18:33], v[194:197], v[206:209], v[18:33]
	s_waitcnt lgkmcnt(6)
	v_mfma_f32_32x32x16_bf16 v[34:49], v[190:193], v[210:213], v[34:49]
	v_mfma_f32_32x32x16_bf16 v[2:17], v[194:197], v[210:213], v[2:17]
	ds_read_b128 v[190:193], v188 offset:64
	ds_read_b128 v[194:197], v188 offset:4672
	ds_read_b128 v[198:201], v189 offset:18496
	ds_read_b128 v[202:205], v189 offset:23104
	ds_read_b128 v[206:209], v189 offset:27712
	ds_read_b128 v[210:213], v189 offset:32320
	s_waitcnt lgkmcnt(9)
	v_mfma_f32_32x32x16_bf16 v[114:129], v[214:217], v[238:241], v[114:129]
	v_mfma_f32_32x32x16_bf16 v[82:97], v[234:237], v[238:241], v[82:97]
	s_waitcnt lgkmcnt(8)
	v_mfma_f32_32x32x16_bf16 v[98:113], v[214:217], v[242:245], v[98:113]
	v_mfma_f32_32x32x16_bf16 v[66:81], v[234:237], v[242:245], v[66:81]
	s_waitcnt lgkmcnt(7)
	v_mfma_f32_32x32x16_bf16 v[50:65], v[214:217], v[246:249], v[50:65]
	v_mfma_f32_32x32x16_bf16 v[18:33], v[234:237], v[246:249], v[18:33]
	s_waitcnt lgkmcnt(6)
	v_mfma_f32_32x32x16_bf16 v[34:49], v[214:217], v[218:221], v[34:49]
	v_mfma_f32_32x32x16_bf16 v[2:17], v[234:237], v[218:221], v[2:17]
	ds_read_b128 v[214:217], v188 offset:96
	ds_read_b128 v[218:221], v188 offset:4704
	ds_read_b128 v[234:237], v189 offset:18528
	ds_read_b128 v[238:241], v189 offset:23136
	ds_read_b128 v[242:245], v189 offset:27744
	ds_read_b128 v[246:249], v189 offset:32352
	s_waitcnt lgkmcnt(9)
	v_mfma_f32_32x32x16_bf16 v[114:129], v[190:193], v[198:201], v[114:129]
	v_mfma_f32_32x32x16_bf16 v[82:97], v[194:197], v[198:201], v[82:97]
	s_waitcnt lgkmcnt(8)
	v_mfma_f32_32x32x16_bf16 v[98:113], v[190:193], v[202:205], v[98:113]
	v_mfma_f32_32x32x16_bf16 v[66:81], v[194:197], v[202:205], v[66:81]
	s_waitcnt lgkmcnt(0)
	s_barrier
	v_mfma_f32_32x32x16_bf16 v[50:65], v[190:193], v[206:209], v[50:65]
	s_waitcnt vmcnt(9)
	ds_write_b128 v187, v[130:133]
	v_mfma_f32_32x32x16_bf16 v[18:33], v[194:197], v[206:209], v[18:33]
	ds_write_b128 v187, v[134:137] offset:4608
	v_mfma_f32_32x32x16_bf16 v[34:49], v[190:193], v[210:213], v[34:49]
	ds_write_b128 v187, v[138:141] offset:9216
	v_mfma_f32_32x32x16_bf16 v[2:17], v[194:197], v[210:213], v[2:17]
	s_waitcnt vmcnt(7)
	ds_write_b128 v187, v[142:145] offset:13824
	v_mfma_f32_32x32x16_bf16 v[114:129], v[214:217], v[234:237], v[114:129]
	ds_write_b128 v187, v[146:149] offset:18432
	v_mfma_f32_32x32x16_bf16 v[82:97], v[218:221], v[234:237], v[82:97]
	s_waitcnt vmcnt(6)
	ds_write_b128 v187, v[150:153] offset:23040
	v_mfma_f32_32x32x16_bf16 v[98:113], v[214:217], v[238:241], v[98:113]
	s_waitcnt vmcnt(5)
	ds_write_b128 v187, v[154:157] offset:27648
	v_mfma_f32_32x32x16_bf16 v[66:81], v[218:221], v[238:241], v[66:81]
	s_waitcnt vmcnt(4)
	ds_write_b128 v187, v[158:161] offset:32256
	v_mfma_f32_32x32x16_bf16 v[50:65], v[214:217], v[242:245], v[50:65]
	s_waitcnt vmcnt(3)
	ds_write_b128 v187, v[162:165] offset:36864
	v_mfma_f32_32x32x16_bf16 v[18:33], v[218:221], v[242:245], v[18:33]
	s_waitcnt vmcnt(2)
	ds_write_b128 v187, v[166:169] offset:41472
	v_mfma_f32_32x32x16_bf16 v[34:49], v[214:217], v[246:249], v[34:49]
	s_waitcnt vmcnt(1)
	ds_write_b128 v187, v[170:173] offset:46080
	v_mfma_f32_32x32x16_bf16 v[2:17], v[218:221], v[246:249], v[2:17]
	s_waitcnt vmcnt(0)
	ds_write_b128 v187, v[174:177] offset:50688
	s_cmpk_eq_i32 s6, 0x700
	s_cbranch_scc1 .Lmy_gnold_0
	v_lshl_add_u64 v[138:139], v[184:185], 0, s[6:7]
	v_add_co_u32_e32 v130, vcc, 0x38a8000, v138
	v_lshl_add_u64 v[170:171], v[182:183], 0, s[6:7]
	s_nop 0
	v_addc_co_u32_e32 v131, vcc, 0, v139, vcc
	v_add_co_u32_e32 v134, vcc, 0x38b8000, v138
	s_nop 1
	v_addc_co_u32_e32 v135, vcc, 0, v139, vcc
	v_add_co_u32_e32 v140, vcc, 0x38c8000, v138
	global_load_dwordx4 v[130:133], v[130:131], off offset:256
	s_nop 0
	global_load_dwordx4 v[134:137], v[134:135], off offset:256
	v_addc_co_u32_e32 v141, vcc, 0, v139, vcc
	v_add_co_u32_e32 v142, vcc, 0x38d8000, v138
	s_nop 1
	v_addc_co_u32_e32 v143, vcc, 0, v139, vcc
	v_add_co_u32_e32 v146, vcc, 0x408000, v170
	global_load_dwordx4 v[138:141], v[140:141], off offset:256
	s_nop 0
	global_load_dwordx4 v[142:145], v[142:143], off offset:256
	v_addc_co_u32_e32 v147, vcc, 0, v171, vcc
	v_add_co_u32_e32 v150, vcc, 0x418000, v170
	s_nop 1
	v_addc_co_u32_e32 v151, vcc, 0, v171, vcc
	v_add_co_u32_e32 v154, vcc, 0x428000, v170
	global_load_dwordx4 v[146:149], v[146:147], off offset:256
	s_nop 0
	global_load_dwordx4 v[150:153], v[150:151], off offset:256
	v_addc_co_u32_e32 v155, vcc, 0, v171, vcc
	v_add_co_u32_e32 v158, vcc, 0x438000, v170
	s_nop 1
	v_addc_co_u32_e32 v159, vcc, 0, v171, vcc
	v_add_co_u32_e32 v162, vcc, 0x448000, v170
	global_load_dwordx4 v[154:157], v[154:155], off offset:256
	s_nop 0
	global_load_dwordx4 v[158:161], v[158:159], off offset:256
	v_addc_co_u32_e32 v163, vcc, 0, v171, vcc
	v_add_co_u32_e32 v166, vcc, 0x458000, v170
	s_nop 1
	v_addc_co_u32_e32 v167, vcc, 0, v171, vcc
	v_add_co_u32_e32 v172, vcc, 0x468000, v170
	global_load_dwordx4 v[162:165], v[162:163], off offset:256
	s_nop 0
	global_load_dwordx4 v[166:169], v[166:167], off offset:256
	v_addc_co_u32_e32 v173, vcc, 0, v171, vcc
	v_add_co_u32_e32 v174, vcc, 0x478000, v170
	s_nop 1
	v_addc_co_u32_e32 v175, vcc, 0, v171, vcc
	global_load_dwordx4 v[170:173], v[172:173], off offset:256
	s_nop 0
	global_load_dwordx4 v[174:177], v[174:175], off offset:256
